# GEMM K-loops: m-major snake inside each 16-MFMA cluster (same-acc pairs; transitions alternate sharing srcB / srcA) on v22
# speedup vs baseline: 1.0138x; 1.0034x over previous
; #define PG8_STAGE(bufoff, gbase, voff) do { _Pragma("unroll") for (int _i = 0; _i < 2; ++_i) \
;         __builtin_amdgcn_global_load_lds((const unsigned*)((const char*)(gbase) + (voff)[_i]), (PG8_LAS unsigned*)(lds + (bufoff) + ldsw + _i * 8192), 16, 0, 0); } while (0)
; #define PG8_LDA(dst, b, h) do { _Pragma("unroll") for (int m = 0; m < 4; ++m) _Pragma("unroll") for (int k = 0; k < 2; ++k) dst[m][k] = *(const PG8_LAS bf16x8*)(lds + PG8_SA(b, h) + aoff + m * 2048 + k * 1024); } while (0)
; #define PG8_LDB(dst, b, h) do { _Pragma("unroll") for (int n = 0; n < 2; ++n) _Pragma("unroll") for (int k = 0; k < 2; ++k) dst[n][k] = *(const PG8_LAS bf16x8*)(lds + PG8_SB(b, h) + boff + n * 2048 + k * 1024); } while (0)
; #define PG8_MMA(ai, bj, At, Bt) do { __builtin_amdgcn_s_setprio(1); _Pragma("unroll") for (int m = 0; m < 4; ++m) _Pragma("unroll") for (int n = 0; n < 2; ++n) _Pragma("unroll") for (int k = 0; k < 2; ++k) \
;         acc[ai][bj][m][n] = __builtin_amdgcn_mfma_f32_16x16x32_bf16(Bt[n][k], At[m][k], acc[ai][bj][m][n], 0, 0, 0); __builtin_amdgcn_s_setprio(0); } while (0)
; #define PG8_WAIT_V(n) asm volatile("s_waitcnt vmcnt(" #n ")" ::: "memory")
; #define PG8_WAIT_L(n) asm volatile("s_waitcnt lgkmcnt(" #n ")" ::: "memory")
; #define PG8_BAR __builtin_amdgcn_s_barrier()
; #define PG8_SCHED __builtin_amdgcn_sched_barrier(0)
; template <class Epi, class Sched, bool ALIGN_EPI = false, bool SP2 = false>
; __device__ __forceinline__ void gemm_phase(PG8_LAS unsigned char* lds, const Gemm g, const Sched& S, const Epi& E) {
;     ...
;             PG8_LDB(B0, 0, 0); PG8_LDB(B1, 0, 1); PG8_SCHED; PG8_LDA(At, 0, 0); PG8_STAGE(PG8_SA(1, 1), a1 + hstep, voffA);
;             PG8_WAIT_V(8); PG8_WAIT_L(0); PG8_BAR; PG8_MMA(0, 0, At, B0); PG8_MMA(0, 1, At, B1); PG8_BAR; PG8_SCHED;
;             PG8_LDA(At, 0, 1); PG8_STAGE(PG8_SB(0, 0), b2, voffB); PG8_STAGE(PG8_SB(0, 1), b2 + hstep, voffB); PG8_STAGE(PG8_SA(0, 0), a2, voffA);
;             PG8_WAIT_V(8); PG8_WAIT_L(0); PG8_BAR; PG8_MMA(1, 0, At, B0); PG8_MMA(1, 1, At, B1); PG8_BAR; PG8_SCHED;
.LBB0_85:
	s_add_u32 s40, s38, 0xfff80080
	s_addc_u32 s41, s39, -1
	s_add_i32 s45, 0, 0x10000
	s_cmp_eq_u32 s44, 28
	s_cselect_b32 s43, s5, s41
	s_cselect_b32 s42, s12, s40
	s_cselect_b32 s41, s23, s37
	s_cselect_b32 s40, s25, s31
	s_add_i32 s48, 0, 0x14000
	v_add_u32_e32 v140, s45, v184
	v_add_u32_e32 v154, s48, v184
	ds_read_b128 v[128:131], v140
	ds_read_b128 v[132:135], v140 offset:1024
	ds_read_b128 v[136:139], v140 offset:2048
	ds_read_b128 v[140:143], v140 offset:3072
	ds_read_b128 v[164:167], v154
	ds_read_b128 v[168:171], v154 offset:1024
	ds_read_b128 v[172:175], v154 offset:2048
	ds_read_b128 v[186:189], v154 offset:3072
	v_lshl_add_u64 v[222:223], s[38:39], 0, v[158:159]
	s_add_i32 m0, s58, 0xc000
	ds_read_b128 v[190:193], v185
	ds_read_b128 v[194:197], v185 offset:1024
	ds_read_b128 v[198:201], v185 offset:2048
	ds_read_b128 v[202:205], v185 offset:3072
	ds_read_b128 v[206:209], v185 offset:4096
	ds_read_b128 v[210:213], v185 offset:5120
	ds_read_b128 v[214:217], v185 offset:6144
	ds_read_b128 v[218:221], v185 offset:7168
	global_load_lds_dwordx4 v[222:223], off
	v_lshl_add_u64 v[222:223], s[38:39], 0, v[160:161]
	s_add_i32 m0, s58, 0xe000
	s_nop 0
	global_load_lds_dwordx4 v[222:223], off
	s_waitcnt vmcnt(8)
	s_waitcnt lgkmcnt(0)
	s_barrier
	s_setprio 1
	s_waitcnt lgkmcnt(0)
	v_mfma_f32_16x16x32_bf16 v[124:127], v[128:131], v[190:193], v[124:127]
	v_mfma_f32_16x16x32_bf16 v[124:127], v[132:135], v[194:197], v[124:127]
	v_mfma_f32_16x16x32_bf16 v[116:119], v[140:143], v[194:197], v[116:119]
	v_mfma_f32_16x16x32_bf16 v[116:119], v[136:139], v[190:193], v[116:119]
	v_mfma_f32_16x16x32_bf16 v[104:107], v[136:139], v[198:201], v[104:107]
	v_mfma_f32_16x16x32_bf16 v[104:107], v[140:143], v[202:205], v[104:107]
	v_mfma_f32_16x16x32_bf16 v[108:111], v[132:135], v[202:205], v[108:111]
	v_mfma_f32_16x16x32_bf16 v[108:111], v[128:131], v[198:201], v[108:111]
	v_mfma_f32_16x16x32_bf16 v[92:95], v[128:131], v[206:209], v[92:95]
	v_mfma_f32_16x16x32_bf16 v[92:95], v[132:135], v[210:213], v[92:95]
	v_mfma_f32_16x16x32_bf16 v[88:91], v[140:143], v[210:213], v[88:91]
	v_mfma_f32_16x16x32_bf16 v[88:91], v[136:139], v[206:209], v[88:91]
	v_mfma_f32_16x16x32_bf16 v[72:75], v[136:139], v[214:217], v[72:75]
	v_mfma_f32_16x16x32_bf16 v[72:75], v[140:143], v[218:221], v[72:75]
	v_mfma_f32_16x16x32_bf16 v[76:79], v[132:135], v[218:221], v[76:79]
	v_mfma_f32_16x16x32_bf16 v[76:79], v[128:131], v[214:217], v[76:79]
	s_setprio 0
	s_setprio 1
	v_mfma_f32_16x16x32_bf16 v[120:123], v[164:167], v[190:193], v[120:123]
	v_mfma_f32_16x16x32_bf16 v[120:123], v[168:171], v[194:197], v[120:123]
	v_mfma_f32_16x16x32_bf16 v[112:115], v[186:189], v[194:197], v[112:115]
	v_mfma_f32_16x16x32_bf16 v[112:115], v[172:175], v[190:193], v[112:115]
	v_mfma_f32_16x16x32_bf16 v[96:99], v[172:175], v[198:201], v[96:99]
	v_mfma_f32_16x16x32_bf16 v[96:99], v[186:189], v[202:205], v[96:99]
	v_mfma_f32_16x16x32_bf16 v[100:103], v[168:171], v[202:205], v[100:103]
	v_mfma_f32_16x16x32_bf16 v[100:103], v[164:167], v[198:201], v[100:103]
	v_mfma_f32_16x16x32_bf16 v[84:87], v[164:167], v[206:209], v[84:87]
	v_mfma_f32_16x16x32_bf16 v[84:87], v[168:171], v[210:213], v[84:87]
	v_mfma_f32_16x16x32_bf16 v[80:83], v[186:189], v[210:213], v[80:83]
	v_mfma_f32_16x16x32_bf16 v[80:83], v[172:175], v[206:209], v[80:83]
	v_mfma_f32_16x16x32_bf16 v[64:67], v[172:175], v[214:217], v[64:67]
	v_mfma_f32_16x16x32_bf16 v[64:67], v[186:189], v[218:221], v[64:67]
	v_mfma_f32_16x16x32_bf16 v[68:71], v[168:171], v[218:221], v[68:71]
	v_mfma_f32_16x16x32_bf16 v[68:71], v[164:167], v[214:217], v[68:71]
	s_setprio 0
	s_barrier
	s_add_i32 s45, s45, s57
	v_lshl_add_u64 v[222:223], s[40:41], 0, v[148:149]
	s_mov_b32 m0, s45
	ds_read_b128 v[190:193], v185 offset:16384
	ds_read_b128 v[194:197], v185 offset:17408
	ds_read_b128 v[198:201], v185 offset:18432
	ds_read_b128 v[202:205], v185 offset:19456
	ds_read_b128 v[206:209], v185 offset:20480
	ds_read_b128 v[210:213], v185 offset:21504
	ds_read_b128 v[214:217], v185 offset:22528
	ds_read_b128 v[218:221], v185 offset:23552
	global_load_lds_dwordx4 v[222:223], off
	s_add_i32 m0, s45, 0x2000
	s_add_u32 s46, s40, 0x80000
	v_lshl_add_u64 v[224:225], s[40:41], 0, v[152:153]
	s_addc_u32 s47, s41, 0
	s_add_i32 s45, s48, s57
	global_load_lds_dwordx4 v[224:225], off
	v_lshl_add_u64 v[226:227], s[46:47], 0, v[148:149]
	s_mov_b32 m0, s45
	v_lshl_add_u64 v[232:233], s[42:43], 0, v[150:151]
	global_load_lds_dwordx4 v[226:227], off
	v_lshl_add_u64 v[226:227], s[46:47], 0, v[152:153]
	s_add_i32 m0, s45, 0x2000
	s_nop 0
	global_load_lds_dwordx4 v[226:227], off
	v_lshl_add_u64 v[226:227], s[42:43], 0, v[146:147]
	s_mov_b32 m0, s58
	s_nop 0
	global_load_lds_dwordx4 v[226:227], off
	s_mov_b32 m0, s59
	s_nop 0
	global_load_lds_dwordx4 v[232:233], off
	s_waitcnt vmcnt(8)
	s_waitcnt lgkmcnt(0)
	s_barrier
; #define PG8_STAGE(bufoff, gbase, voff) do { _Pragma("unroll") for (int _i = 0; _i < 2; ++_i) \
;         __builtin_amdgcn_global_load_lds((const unsigned*)((const char*)(gbase) + (voff)[_i]), (PG8_LAS unsigned*)(lds + (bufoff) + ldsw + _i * 8192), 16, 0, 0); } while (0)
; #define PG8_LDA(dst, b, h) do { _Pragma("unroll") for (int m = 0; m < 4; ++m) _Pragma("unroll") for (int k = 0; k < 2; ++k) dst[m][k] = *(const PG8_LAS bf16x8*)(lds + PG8_SA(b, h) + aoff + m * 2048 + k * 1024); } while (0)
; #define PG8_LDB(dst, b, h) do { _Pragma("unroll") for (int n = 0; n < 2; ++n) _Pragma("unroll") for (int k = 0; k < 2; ++k) dst[n][k] = *(const PG8_LAS bf16x8*)(lds + PG8_SB(b, h) + boff + n * 2048 + k * 1024); } while (0)
; #define PG8_MMA(ai, bj, At, Bt) do { __builtin_amdgcn_s_setprio(1); _Pragma("unroll") for (int m = 0; m < 4; ++m) _Pragma("unroll") for (int n = 0; n < 2; ++n) _Pragma("unroll") for (int k = 0; k < 2; ++k) \
;         acc[ai][bj][m][n] = __builtin_amdgcn_mfma_f32_16x16x32_bf16(Bt[n][k], At[m][k], acc[ai][bj][m][n], 0, 0, 0); __builtin_amdgcn_s_setprio(0); } while (0)
; #define PG8_WAIT_V(n) asm volatile("s_waitcnt vmcnt(" #n ")" ::: "memory")
; #define PG8_WAIT_L(n) asm volatile("s_waitcnt lgkmcnt(" #n ")" ::: "memory")
; #define PG8_BAR __builtin_amdgcn_s_barrier()
; #define PG8_SCHED __builtin_amdgcn_sched_barrier(0)
; template <class Epi, class Sched, bool ALIGN_EPI = false, bool SP2 = false>
; __device__ __forceinline__ void gemm_phase(PG8_LAS unsigned char* lds, const Gemm g, const Sched& S, const Epi& E) {
;     ...
;             PG8_WAIT_V(8); PG8_WAIT_L(0); PG8_BAR; PG8_MMA(1, 0, At, B0); PG8_MMA(1, 1, At, B1); PG8_BAR; PG8_SCHED;
;             PG8_LDB(B0, 1, 0); PG8_LDB(B1, 1, 1); PG8_SCHED; PG8_LDA(At, 1, 0); PG8_STAGE(PG8_SA(0, 1), a2 + hstep, voffA);
;             PG8_WAIT_V(8); PG8_WAIT_L(0); PG8_BAR; PG8_MMA(0, 0, At, B0); PG8_MMA(0, 1, At, B1); PG8_BAR; PG8_SCHED;
	s_setprio 1
	s_waitcnt lgkmcnt(0)
	v_mfma_f32_16x16x32_bf16 v[60:63], v[128:131], v[190:193], v[60:63]
	v_mfma_f32_16x16x32_bf16 v[60:63], v[132:135], v[194:197], v[60:63]
	v_mfma_f32_16x16x32_bf16 v[56:59], v[140:143], v[194:197], v[56:59]
	v_mfma_f32_16x16x32_bf16 v[56:59], v[136:139], v[190:193], v[56:59]
	v_mfma_f32_16x16x32_bf16 v[40:43], v[136:139], v[198:201], v[40:43]
	v_mfma_f32_16x16x32_bf16 v[40:43], v[140:143], v[202:205], v[40:43]
	v_mfma_f32_16x16x32_bf16 v[44:47], v[132:135], v[202:205], v[44:47]
	v_mfma_f32_16x16x32_bf16 v[44:47], v[128:131], v[198:201], v[44:47]
	v_mfma_f32_16x16x32_bf16 v[28:31], v[128:131], v[206:209], v[28:31]
	v_mfma_f32_16x16x32_bf16 v[28:31], v[132:135], v[210:213], v[28:31]
	v_mfma_f32_16x16x32_bf16 v[24:27], v[140:143], v[210:213], v[24:27]
	v_mfma_f32_16x16x32_bf16 v[24:27], v[136:139], v[206:209], v[24:27]
	v_mfma_f32_16x16x32_bf16 v[8:11], v[136:139], v[214:217], v[8:11]
	v_mfma_f32_16x16x32_bf16 v[8:11], v[140:143], v[218:221], v[8:11]
	v_mfma_f32_16x16x32_bf16 v[12:15], v[132:135], v[218:221], v[12:15]
	v_mfma_f32_16x16x32_bf16 v[12:15], v[128:131], v[214:217], v[12:15]
	s_setprio 0
	s_setprio 1
	v_mfma_f32_16x16x32_bf16 v[52:55], v[164:167], v[190:193], v[52:55]
	v_mfma_f32_16x16x32_bf16 v[52:55], v[168:171], v[194:197], v[52:55]
	v_mfma_f32_16x16x32_bf16 v[48:51], v[186:189], v[194:197], v[48:51]
	v_mfma_f32_16x16x32_bf16 v[48:51], v[172:175], v[190:193], v[48:51]
	v_mfma_f32_16x16x32_bf16 v[32:35], v[172:175], v[198:201], v[32:35]
	v_mfma_f32_16x16x32_bf16 v[32:35], v[186:189], v[202:205], v[32:35]
	v_mfma_f32_16x16x32_bf16 v[36:39], v[168:171], v[202:205], v[36:39]
	v_mfma_f32_16x16x32_bf16 v[36:39], v[164:167], v[198:201], v[36:39]
	v_mfma_f32_16x16x32_bf16 v[20:23], v[164:167], v[206:209], v[20:23]
	v_mfma_f32_16x16x32_bf16 v[20:23], v[168:171], v[210:213], v[20:23]
	v_mfma_f32_16x16x32_bf16 v[16:19], v[186:189], v[210:213], v[16:19]
	v_mfma_f32_16x16x32_bf16 v[16:19], v[172:175], v[206:209], v[16:19]
	v_mfma_f32_16x16x32_bf16 v[0:3], v[172:175], v[214:217], v[0:3]
	v_mfma_f32_16x16x32_bf16 v[0:3], v[186:189], v[218:221], v[0:3]
	v_mfma_f32_16x16x32_bf16 v[4:7], v[168:171], v[218:221], v[4:7]
	v_mfma_f32_16x16x32_bf16 v[4:7], v[164:167], v[214:217], v[4:7]
	s_setprio 0
	s_barrier
	s_add_i32 s45, 0, 0x18000
	s_add_i32 s46, 0, 0x1c000
	v_add_u32_e32 v140, s45, v184
	v_add_u32_e32 v154, s46, v184
	ds_read_b128 v[128:131], v140
	ds_read_b128 v[132:135], v140 offset:1024
	ds_read_b128 v[136:139], v140 offset:2048
	ds_read_b128 v[140:143], v140 offset:3072
	ds_read_b128 v[164:167], v154
	ds_read_b128 v[168:171], v154 offset:1024
	ds_read_b128 v[172:175], v154 offset:2048
	ds_read_b128 v[186:189], v154 offset:3072
	s_add_u32 s42, s42, 0x80000
	s_addc_u32 s43, s43, 0
	s_mov_b32 m0, s60
	v_lshl_add_u64 v[234:235], s[42:43], 0, v[146:147]
	ds_read_b128 v[190:193], v185 offset:32768
	ds_read_b128 v[194:197], v185 offset:33792
	ds_read_b128 v[198:201], v185 offset:34816
	ds_read_b128 v[202:205], v185 offset:35840
	ds_read_b128 v[206:209], v185 offset:36864
	ds_read_b128 v[210:213], v185 offset:37888
	ds_read_b128 v[214:217], v185 offset:38912
	ds_read_b128 v[218:221], v185 offset:39936
	global_load_lds_dwordx4 v[234:235], off
	v_lshl_add_u64 v[234:235], s[42:43], 0, v[150:151]
	s_mov_b32 m0, s61
	s_nop 0
	global_load_lds_dwordx4 v[234:235], off
	s_waitcnt vmcnt(8)
	s_waitcnt lgkmcnt(0)
	s_barrier
	s_setprio 1
	s_waitcnt lgkmcnt(0)
	v_mfma_f32_16x16x32_bf16 v[124:127], v[128:131], v[190:193], v[124:127]
	v_mfma_f32_16x16x32_bf16 v[124:127], v[132:135], v[194:197], v[124:127]
	v_mfma_f32_16x16x32_bf16 v[116:119], v[140:143], v[194:197], v[116:119]
	v_mfma_f32_16x16x32_bf16 v[116:119], v[136:139], v[190:193], v[116:119]
	v_mfma_f32_16x16x32_bf16 v[104:107], v[136:139], v[198:201], v[104:107]
	v_mfma_f32_16x16x32_bf16 v[104:107], v[140:143], v[202:205], v[104:107]
	v_mfma_f32_16x16x32_bf16 v[108:111], v[132:135], v[202:205], v[108:111]
	v_mfma_f32_16x16x32_bf16 v[108:111], v[128:131], v[198:201], v[108:111]
	v_mfma_f32_16x16x32_bf16 v[92:95], v[128:131], v[206:209], v[92:95]
	v_mfma_f32_16x16x32_bf16 v[92:95], v[132:135], v[210:213], v[92:95]
	v_mfma_f32_16x16x32_bf16 v[88:91], v[140:143], v[210:213], v[88:91]
	v_mfma_f32_16x16x32_bf16 v[88:91], v[136:139], v[206:209], v[88:91]
	v_mfma_f32_16x16x32_bf16 v[72:75], v[136:139], v[214:217], v[72:75]
	v_mfma_f32_16x16x32_bf16 v[72:75], v[140:143], v[218:221], v[72:75]
	v_mfma_f32_16x16x32_bf16 v[76:79], v[132:135], v[218:221], v[76:79]
	v_mfma_f32_16x16x32_bf16 v[76:79], v[128:131], v[214:217], v[76:79]
	s_setprio 0
	s_setprio 1
	v_mfma_f32_16x16x32_bf16 v[120:123], v[164:167], v[190:193], v[120:123]
	v_mfma_f32_16x16x32_bf16 v[120:123], v[168:171], v[194:197], v[120:123]
	v_mfma_f32_16x16x32_bf16 v[112:115], v[186:189], v[194:197], v[112:115]
	v_mfma_f32_16x16x32_bf16 v[112:115], v[172:175], v[190:193], v[112:115]
	v_mfma_f32_16x16x32_bf16 v[96:99], v[172:175], v[198:201], v[96:99]
	v_mfma_f32_16x16x32_bf16 v[96:99], v[186:189], v[202:205], v[96:99]
	v_mfma_f32_16x16x32_bf16 v[100:103], v[168:171], v[202:205], v[100:103]
	v_mfma_f32_16x16x32_bf16 v[100:103], v[164:167], v[198:201], v[100:103]
	v_mfma_f32_16x16x32_bf16 v[84:87], v[164:167], v[206:209], v[84:87]
	v_mfma_f32_16x16x32_bf16 v[84:87], v[168:171], v[210:213], v[84:87]
	v_mfma_f32_16x16x32_bf16 v[80:83], v[186:189], v[210:213], v[80:83]
	v_mfma_f32_16x16x32_bf16 v[80:83], v[172:175], v[206:209], v[80:83]
	v_mfma_f32_16x16x32_bf16 v[64:67], v[172:175], v[214:217], v[64:67]
	v_mfma_f32_16x16x32_bf16 v[64:67], v[186:189], v[218:221], v[64:67]
	v_mfma_f32_16x16x32_bf16 v[68:71], v[168:171], v[218:221], v[68:71]
	v_mfma_f32_16x16x32_bf16 v[68:71], v[164:167], v[214:217], v[68:71]
	s_setprio 0
	s_barrier
; #define PG8_STAGE(bufoff, gbase, voff) do { _Pragma("unroll") for (int _i = 0; _i < 2; ++_i) \
;         __builtin_amdgcn_global_load_lds((const unsigned*)((const char*)(gbase) + (voff)[_i]), (PG8_LAS unsigned*)(lds + (bufoff) + ldsw + _i * 8192), 16, 0, 0); } while (0)
; #define PG8_LDA(dst, b, h) do { _Pragma("unroll") for (int m = 0; m < 4; ++m) _Pragma("unroll") for (int k = 0; k < 2; ++k) dst[m][k] = *(const PG8_LAS bf16x8*)(lds + PG8_SA(b, h) + aoff + m * 2048 + k * 1024); } while (0)
; #define PG8_MMA(ai, bj, At, Bt) do { __builtin_amdgcn_s_setprio(1); _Pragma("unroll") for (int m = 0; m < 4; ++m) _Pragma("unroll") for (int n = 0; n < 2; ++n) _Pragma("unroll") for (int k = 0; k < 2; ++k) \
;         acc[ai][bj][m][n] = __builtin_amdgcn_mfma_f32_16x16x32_bf16(Bt[n][k], At[m][k], acc[ai][bj][m][n], 0, 0, 0); __builtin_amdgcn_s_setprio(0); } while (0)
; #define PG8_WAIT_V(n) asm volatile("s_waitcnt vmcnt(" #n ")" ::: "memory")
; #define PG8_WAIT_L(n) asm volatile("s_waitcnt lgkmcnt(" #n ")" ::: "memory")
; #define PG8_BAR __builtin_amdgcn_s_barrier()
; #define PG8_SCHED __builtin_amdgcn_sched_barrier(0)
; template <class Epi, class Sched, bool ALIGN_EPI = false, bool SP2 = false>
; __device__ __forceinline__ void gemm_phase(PG8_LAS unsigned char* lds, const Gemm g, const Sched& S, const Epi& E) {
;     ...
;         for (int t = 0; t < nt; t += 2) {
;     ...
;             PG8_LDA(At, 1, 1); PG8_STAGE(PG8_SB(1, 0), b3, voffB); PG8_STAGE(PG8_SB(1, 1), b3 + hstep, voffB); PG8_STAGE(PG8_SA(1, 0), a3, voffA);
;             PG8_WAIT_V(8); PG8_WAIT_L(0); PG8_BAR; PG8_MMA(1, 0, At, B0); PG8_MMA(1, 1, At, B1); PG8_BAR; PG8_SCHED;
	s_add_i32 s42, s45, s57
	v_lshl_add_u64 v[222:223], v[222:223], 0, s[14:15]
	s_mov_b32 m0, s42
	ds_read_b128 v[190:193], v185 offset:49152
	ds_read_b128 v[194:197], v185 offset:50176
	ds_read_b128 v[198:201], v185 offset:51200
	ds_read_b128 v[202:205], v185 offset:52224
	ds_read_b128 v[206:209], v185 offset:53248
	ds_read_b128 v[210:213], v185 offset:54272
	ds_read_b128 v[214:217], v185 offset:55296
	ds_read_b128 v[218:221], v185 offset:56320
	global_load_lds_dwordx4 v[222:223], off
	s_add_i32 m0, s42, 0x2000
	s_add_u32 s40, s40, 0x80080
	v_lshl_add_u64 v[222:223], v[224:225], 0, s[14:15]
	s_addc_u32 s41, s41, 0
	s_add_i32 s42, s46, s57
	global_load_lds_dwordx4 v[222:223], off
	v_lshl_add_u64 v[222:223], s[40:41], 0, v[148:149]
	s_mov_b32 m0, s42
	s_nop 0
	global_load_lds_dwordx4 v[222:223], off
	v_lshl_add_u64 v[222:223], s[40:41], 0, v[152:153]
	s_add_i32 m0, s42, 0x2000
	s_nop 0
	global_load_lds_dwordx4 v[222:223], off
	v_lshl_add_u64 v[222:223], v[226:227], 0, s[14:15]
	s_mov_b32 m0, s63
	s_nop 0
	global_load_lds_dwordx4 v[222:223], off
	v_lshl_add_u64 v[222:223], v[232:233], 0, s[14:15]
	s_mov_b32 m0, s64
	s_nop 0
	global_load_lds_dwordx4 v[222:223], off
	s_waitcnt vmcnt(8)
	s_waitcnt lgkmcnt(0)
	s_barrier
	s_setprio 1
	s_waitcnt lgkmcnt(0)
	v_mfma_f32_16x16x32_bf16 v[60:63], v[128:131], v[190:193], v[60:63]
	v_mfma_f32_16x16x32_bf16 v[60:63], v[132:135], v[194:197], v[60:63]
	v_mfma_f32_16x16x32_bf16 v[56:59], v[140:143], v[194:197], v[56:59]
	v_mfma_f32_16x16x32_bf16 v[56:59], v[136:139], v[190:193], v[56:59]
	v_mfma_f32_16x16x32_bf16 v[40:43], v[136:139], v[198:201], v[40:43]
	v_mfma_f32_16x16x32_bf16 v[40:43], v[140:143], v[202:205], v[40:43]
	v_mfma_f32_16x16x32_bf16 v[44:47], v[132:135], v[202:205], v[44:47]
	v_mfma_f32_16x16x32_bf16 v[44:47], v[128:131], v[198:201], v[44:47]
	v_mfma_f32_16x16x32_bf16 v[28:31], v[128:131], v[206:209], v[28:31]
	v_mfma_f32_16x16x32_bf16 v[28:31], v[132:135], v[210:213], v[28:31]
	v_mfma_f32_16x16x32_bf16 v[24:27], v[140:143], v[210:213], v[24:27]
	v_mfma_f32_16x16x32_bf16 v[24:27], v[136:139], v[206:209], v[24:27]
	v_mfma_f32_16x16x32_bf16 v[8:11], v[136:139], v[214:217], v[8:11]
	v_mfma_f32_16x16x32_bf16 v[8:11], v[140:143], v[218:221], v[8:11]
	v_mfma_f32_16x16x32_bf16 v[12:15], v[132:135], v[218:221], v[12:15]
	v_mfma_f32_16x16x32_bf16 v[12:15], v[128:131], v[214:217], v[12:15]
	s_setprio 0
	s_setprio 1
	v_mfma_f32_16x16x32_bf16 v[52:55], v[164:167], v[190:193], v[52:55]
	v_mfma_f32_16x16x32_bf16 v[52:55], v[168:171], v[194:197], v[52:55]
	v_mfma_f32_16x16x32_bf16 v[48:51], v[186:189], v[194:197], v[48:51]
	v_mfma_f32_16x16x32_bf16 v[48:51], v[172:175], v[190:193], v[48:51]
	v_mfma_f32_16x16x32_bf16 v[32:35], v[172:175], v[198:201], v[32:35]
	v_mfma_f32_16x16x32_bf16 v[32:35], v[186:189], v[202:205], v[32:35]
	v_mfma_f32_16x16x32_bf16 v[36:39], v[168:171], v[202:205], v[36:39]
	v_mfma_f32_16x16x32_bf16 v[36:39], v[164:167], v[198:201], v[36:39]
	v_mfma_f32_16x16x32_bf16 v[20:23], v[164:167], v[206:209], v[20:23]
	v_mfma_f32_16x16x32_bf16 v[20:23], v[168:171], v[210:213], v[20:23]
	v_mfma_f32_16x16x32_bf16 v[16:19], v[186:189], v[210:213], v[16:19]
	v_mfma_f32_16x16x32_bf16 v[16:19], v[172:175], v[206:209], v[16:19]
	v_mfma_f32_16x16x32_bf16 v[0:3], v[172:175], v[214:217], v[0:3]
	v_mfma_f32_16x16x32_bf16 v[0:3], v[186:189], v[218:221], v[0:3]
	v_mfma_f32_16x16x32_bf16 v[4:7], v[168:171], v[218:221], v[4:7]
	v_mfma_f32_16x16x32_bf16 v[4:7], v[164:167], v[214:217], v[4:7]
	s_setprio 0
	s_barrier
	s_add_i32 s44, s44, 2
	s_add_u32 s38, s38, 0x100
	s_addc_u32 s39, s39, 0
	s_add_u32 s31, s31, 0x100
	s_addc_u32 s37, s37, 0
	s_cmp_gt_u32 s44, 29
	s_cbranch_scc0 .LBB0_85
	s_and_b64 vcc, exec, s[20:21]
	s_cbranch_vccz .LBB0_88
	s_barrier

; #define PG8_STAGE(bufoff, gbase, voff) do { _Pragma("unroll") for (int _i = 0; _i < 2; ++_i) \
;         __builtin_amdgcn_global_load_lds((const unsigned*)((const char*)(gbase) + (voff)[_i]), (PG8_LAS unsigned*)(lds + (bufoff) + ldsw + _i * 8192), 16, 0, 0); } while (0)
; #define PG8_LDA(dst, b, h) do { _Pragma("unroll") for (int m = 0; m < 4; ++m) _Pragma("unroll") for (int k = 0; k < 2; ++k) dst[m][k] = *(const PG8_LAS bf16x8*)(lds + PG8_SA(b, h) + aoff + m * 2048 + k * 1024); } while (0)
; #define PG8_LDB(dst, b, h) do { _Pragma("unroll") for (int n = 0; n < 2; ++n) _Pragma("unroll") for (int k = 0; k < 2; ++k) dst[n][k] = *(const PG8_LAS bf16x8*)(lds + PG8_SB(b, h) + boff + n * 2048 + k * 1024); } while (0)
; #define PG8_MMA(ai, bj, At, Bt) do { __builtin_amdgcn_s_setprio(1); _Pragma("unroll") for (int m = 0; m < 4; ++m) _Pragma("unroll") for (int n = 0; n < 2; ++n) _Pragma("unroll") for (int k = 0; k < 2; ++k) \
;         acc[ai][bj][m][n] = __builtin_amdgcn_mfma_f32_16x16x32_bf16(Bt[n][k], At[m][k], acc[ai][bj][m][n], 0, 0, 0); __builtin_amdgcn_s_setprio(0); } while (0)
; #define PG8_WAIT_V(n) asm volatile("s_waitcnt vmcnt(" #n ")" ::: "memory")
; #define PG8_WAIT_L(n) asm volatile("s_waitcnt lgkmcnt(" #n ")" ::: "memory")
; template <class Epi, class Sched, bool ALIGN_EPI = false, bool SP2 = false>
; __device__ __forceinline__ void gemm_phase(PG8_LAS unsigned char* lds, const Gemm g, const Sched& S, const Epi& E) {
;     ...
;             const bool last = (t == nt - 2);
;             const char* a1 = cA + (size_t)(t + 1) * kstep;
;             const char* a2 = last ? nA : cA + (size_t)(t + 2) * kstep; const char* b2 = last ? nB : cB + (size_t)(t + 2) * kstep;
;             const char* a3 = a2 + kstep; const char* b3 = b2 + kstep;
;             if (last && has_next) S.a_ready(nxt);
;             if constexpr (SP2) {
;             PG8_LDB(B0, 0, 0); PG8_LDB(B1, 0, 1); PG8_SCHED; PG8_LDA(At, 0, 0); PG8_STAGE(PG8_SA(1, 1), a1 + hstep, voffA);
;             PG8_WAIT_V(8); PG8_WAIT_L(0); PG8_BAR; PG8_MMA(0, 0, At, B0); PG8_MMA(0, 1, At, B1); PG8_BAR; PG8_SCHED;
;             PG8_LDA(At, 0, 1); PG8_STAGE(PG8_SB(0, 0), b2, voffB); PG8_STAGE(PG8_SB(0, 1), b2 + hstep, voffB); PG8_STAGE(PG8_SA(0, 0), a2, voffA);
;             PG8_WAIT_V(8); PG8_WAIT_L(0); PG8_BAR; PG8_MMA(1, 0, At, B0); PG8_MMA(1, 1, At, B1); PG8_BAR; PG8_SCHED;
.LBB0_458:
	ds_read_b128 v[140:143], v149
	ds_read_b128 v[152:155], v149 offset:1024
	ds_read_b128 v[156:159], v149 offset:2048
	ds_read_b128 v[160:163], v149 offset:3072
	ds_read_b128 v[164:167], v150
	ds_read_b128 v[168:171], v150 offset:1024
	ds_read_b128 v[172:175], v150 offset:2048
	ds_read_b128 v[176:179], v150 offset:3072
	s_add_u32 s28, s26, 0xfff80080
	s_addc_u32 s29, s27, -1
	s_cmp_eq_u32 s49, 28
	s_cselect_b32 s35, s19, s29
	s_cselect_b32 s34, s31, s28
	s_cselect_b32 s29, s17, s48
	s_cselect_b32 s28, s46, s47
	v_lshl_add_u64 v[144:145], s[26:27], 0, v[132:133]
	s_add_i32 m0, s25, 0xc000
	ds_read_b128 v[180:183], v151
	ds_read_b128 v[184:187], v151 offset:1024
	ds_read_b128 v[188:191], v151 offset:2048
	ds_read_b128 v[192:195], v151 offset:3072
	ds_read_b128 v[196:199], v151 offset:4096
	ds_read_b128 v[200:203], v151 offset:5120
	ds_read_b128 v[204:207], v151 offset:6144
	ds_read_b128 v[208:211], v151 offset:7168
	global_load_lds_dwordx4 v[144:145], off
	v_lshl_add_u64 v[144:145], s[26:27], 0, v[134:135]
	s_add_i32 m0, s25, 0xe000
	s_nop 0
	global_load_lds_dwordx4 v[144:145], off
	s_waitcnt vmcnt(8)
	s_waitcnt lgkmcnt(0)
	s_barrier
	s_setprio 1
	s_waitcnt lgkmcnt(0)
	v_mfma_f32_16x16x32_bf16 v[124:127], v[140:143], v[180:183], v[124:127]
	v_mfma_f32_16x16x32_bf16 v[124:127], v[152:155], v[184:187], v[124:127]
	v_mfma_f32_16x16x32_bf16 v[120:123], v[160:163], v[184:187], v[120:123]
	v_mfma_f32_16x16x32_bf16 v[120:123], v[156:159], v[180:183], v[120:123]
	v_mfma_f32_16x16x32_bf16 v[112:115], v[156:159], v[188:191], v[112:115]
	v_mfma_f32_16x16x32_bf16 v[112:115], v[160:163], v[192:195], v[112:115]
	v_mfma_f32_16x16x32_bf16 v[116:119], v[152:155], v[192:195], v[116:119]
	v_mfma_f32_16x16x32_bf16 v[116:119], v[140:143], v[188:191], v[116:119]
	v_mfma_f32_16x16x32_bf16 v[108:111], v[140:143], v[196:199], v[108:111]
	v_mfma_f32_16x16x32_bf16 v[108:111], v[152:155], v[200:203], v[108:111]
	v_mfma_f32_16x16x32_bf16 v[100:103], v[160:163], v[200:203], v[100:103]
	v_mfma_f32_16x16x32_bf16 v[100:103], v[156:159], v[196:199], v[100:103]
	v_mfma_f32_16x16x32_bf16 v[80:83], v[156:159], v[204:207], v[80:83]
	v_mfma_f32_16x16x32_bf16 v[80:83], v[160:163], v[208:211], v[80:83]
	v_mfma_f32_16x16x32_bf16 v[92:95], v[152:155], v[208:211], v[92:95]
	v_mfma_f32_16x16x32_bf16 v[92:95], v[140:143], v[204:207], v[92:95]
	s_setprio 0
	s_setprio 1
	v_mfma_f32_16x16x32_bf16 v[104:107], v[164:167], v[180:183], v[104:107]
	v_mfma_f32_16x16x32_bf16 v[104:107], v[168:171], v[184:187], v[104:107]
	v_mfma_f32_16x16x32_bf16 v[96:99], v[176:179], v[184:187], v[96:99]
	v_mfma_f32_16x16x32_bf16 v[96:99], v[172:175], v[180:183], v[96:99]
	v_mfma_f32_16x16x32_bf16 v[84:87], v[172:175], v[188:191], v[84:87]
	v_mfma_f32_16x16x32_bf16 v[84:87], v[176:179], v[192:195], v[84:87]
	v_mfma_f32_16x16x32_bf16 v[88:91], v[168:171], v[192:195], v[88:91]
	v_mfma_f32_16x16x32_bf16 v[88:91], v[164:167], v[188:191], v[88:91]
	v_mfma_f32_16x16x32_bf16 v[76:79], v[164:167], v[196:199], v[76:79]
	v_mfma_f32_16x16x32_bf16 v[76:79], v[168:171], v[200:203], v[76:79]
	v_mfma_f32_16x16x32_bf16 v[72:75], v[176:179], v[200:203], v[72:75]
	v_mfma_f32_16x16x32_bf16 v[72:75], v[172:175], v[196:199], v[72:75]
	v_mfma_f32_16x16x32_bf16 v[64:67], v[172:175], v[204:207], v[64:67]
	v_mfma_f32_16x16x32_bf16 v[64:67], v[176:179], v[208:211], v[64:67]
	v_mfma_f32_16x16x32_bf16 v[68:71], v[168:171], v[208:211], v[68:71]
	v_mfma_f32_16x16x32_bf16 v[68:71], v[164:167], v[204:207], v[68:71]
	s_setprio 0
	s_barrier
	s_add_i32 s50, s43, s30
	v_lshl_add_u64 v[144:145], s[28:29], 0, v[128:129]
	s_mov_b32 m0, s50
	ds_read_b128 v[180:183], v151 offset:16384
	ds_read_b128 v[184:187], v151 offset:17408
	ds_read_b128 v[188:191], v151 offset:18432
	ds_read_b128 v[192:195], v151 offset:19456
	ds_read_b128 v[196:199], v151 offset:20480
	ds_read_b128 v[200:203], v151 offset:21504
	ds_read_b128 v[204:207], v151 offset:22528
	ds_read_b128 v[208:211], v151 offset:23552
	global_load_lds_dwordx4 v[144:145], off
	s_add_i32 m0, s50, 0x2000
	s_add_u32 s50, s28, 0x80000
	v_lshl_add_u64 v[212:213], s[28:29], 0, v[130:131]
	s_addc_u32 s51, s29, 0
	s_add_i32 s52, s44, s30
	global_load_lds_dwordx4 v[212:213], off
	v_lshl_add_u64 v[214:215], s[50:51], 0, v[128:129]
	s_mov_b32 m0, s52
	v_lshl_add_u64 v[216:217], s[34:35], 0, v[130:131]
	global_load_lds_dwordx4 v[214:215], off
	v_lshl_add_u64 v[214:215], s[50:51], 0, v[130:131]
	s_add_i32 m0, s52, 0x2000
	s_nop 0
	global_load_lds_dwordx4 v[214:215], off
	v_lshl_add_u64 v[214:215], s[34:35], 0, v[128:129]
	s_mov_b32 m0, s25
	s_nop 0
	global_load_lds_dwordx4 v[214:215], off
	s_mov_b32 m0, s36
	s_nop 0
	global_load_lds_dwordx4 v[216:217], off
	s_waitcnt vmcnt(8)
	s_waitcnt lgkmcnt(0)
	s_barrier
; #define PG8_STAGE(bufoff, gbase, voff) do { _Pragma("unroll") for (int _i = 0; _i < 2; ++_i) \
;         __builtin_amdgcn_global_load_lds((const unsigned*)((const char*)(gbase) + (voff)[_i]), (PG8_LAS unsigned*)(lds + (bufoff) + ldsw + _i * 8192), 16, 0, 0); } while (0)
; #define PG8_LDA(dst, b, h) do { _Pragma("unroll") for (int m = 0; m < 4; ++m) _Pragma("unroll") for (int k = 0; k < 2; ++k) dst[m][k] = *(const PG8_LAS bf16x8*)(lds + PG8_SA(b, h) + aoff + m * 2048 + k * 1024); } while (0)
; #define PG8_LDB(dst, b, h) do { _Pragma("unroll") for (int n = 0; n < 2; ++n) _Pragma("unroll") for (int k = 0; k < 2; ++k) dst[n][k] = *(const PG8_LAS bf16x8*)(lds + PG8_SB(b, h) + boff + n * 2048 + k * 1024); } while (0)
; #define PG8_MMA(ai, bj, At, Bt) do { __builtin_amdgcn_s_setprio(1); _Pragma("unroll") for (int m = 0; m < 4; ++m) _Pragma("unroll") for (int n = 0; n < 2; ++n) _Pragma("unroll") for (int k = 0; k < 2; ++k) \
;         acc[ai][bj][m][n] = __builtin_amdgcn_mfma_f32_16x16x32_bf16(Bt[n][k], At[m][k], acc[ai][bj][m][n], 0, 0, 0); __builtin_amdgcn_s_setprio(0); } while (0)
; #define PG8_WAIT_V(n) asm volatile("s_waitcnt vmcnt(" #n ")" ::: "memory")
; #define PG8_WAIT_L(n) asm volatile("s_waitcnt lgkmcnt(" #n ")" ::: "memory")
; #define PG8_BAR __builtin_amdgcn_s_barrier()
; #define PG8_SCHED __builtin_amdgcn_sched_barrier(0)
; template <class Epi, class Sched, bool ALIGN_EPI = false, bool SP2 = false>
; __device__ __forceinline__ void gemm_phase(PG8_LAS unsigned char* lds, const Gemm g, const Sched& S, const Epi& E) {
;     ...
;             PG8_WAIT_V(8); PG8_WAIT_L(0); PG8_BAR; PG8_MMA(1, 0, At, B0); PG8_MMA(1, 1, At, B1); PG8_BAR; PG8_SCHED;
;             PG8_LDB(B0, 1, 0); PG8_LDB(B1, 1, 1); PG8_SCHED; PG8_LDA(At, 1, 0); PG8_STAGE(PG8_SA(0, 1), a2 + hstep, voffA);
;             PG8_WAIT_V(8); PG8_WAIT_L(0); PG8_BAR; PG8_MMA(0, 0, At, B0); PG8_MMA(0, 1, At, B1); PG8_BAR; PG8_SCHED;
	s_setprio 1
	s_waitcnt lgkmcnt(0)
	v_mfma_f32_16x16x32_bf16 v[60:63], v[140:143], v[180:183], v[60:63]
	v_mfma_f32_16x16x32_bf16 v[60:63], v[152:155], v[184:187], v[60:63]
	v_mfma_f32_16x16x32_bf16 v[56:59], v[160:163], v[184:187], v[56:59]
	v_mfma_f32_16x16x32_bf16 v[56:59], v[156:159], v[180:183], v[56:59]
	v_mfma_f32_16x16x32_bf16 v[48:51], v[156:159], v[188:191], v[48:51]
	v_mfma_f32_16x16x32_bf16 v[48:51], v[160:163], v[192:195], v[48:51]
	v_mfma_f32_16x16x32_bf16 v[52:55], v[152:155], v[192:195], v[52:55]
	v_mfma_f32_16x16x32_bf16 v[52:55], v[140:143], v[188:191], v[52:55]
	v_mfma_f32_16x16x32_bf16 v[44:47], v[140:143], v[196:199], v[44:47]
	v_mfma_f32_16x16x32_bf16 v[44:47], v[152:155], v[200:203], v[44:47]
	v_mfma_f32_16x16x32_bf16 v[36:39], v[160:163], v[200:203], v[36:39]
	v_mfma_f32_16x16x32_bf16 v[36:39], v[156:159], v[196:199], v[36:39]
	v_mfma_f32_16x16x32_bf16 v[16:19], v[156:159], v[204:207], v[16:19]
	v_mfma_f32_16x16x32_bf16 v[16:19], v[160:163], v[208:211], v[16:19]
	v_mfma_f32_16x16x32_bf16 v[28:31], v[152:155], v[208:211], v[28:31]
	v_mfma_f32_16x16x32_bf16 v[28:31], v[140:143], v[204:207], v[28:31]
	s_setprio 0
	s_setprio 1
	v_mfma_f32_16x16x32_bf16 v[40:43], v[164:167], v[180:183], v[40:43]
	v_mfma_f32_16x16x32_bf16 v[40:43], v[168:171], v[184:187], v[40:43]
	v_mfma_f32_16x16x32_bf16 v[32:35], v[176:179], v[184:187], v[32:35]
	v_mfma_f32_16x16x32_bf16 v[32:35], v[172:175], v[180:183], v[32:35]
	v_mfma_f32_16x16x32_bf16 v[20:23], v[172:175], v[188:191], v[20:23]
	v_mfma_f32_16x16x32_bf16 v[20:23], v[176:179], v[192:195], v[20:23]
	v_mfma_f32_16x16x32_bf16 v[24:27], v[168:171], v[192:195], v[24:27]
	v_mfma_f32_16x16x32_bf16 v[24:27], v[164:167], v[188:191], v[24:27]
	v_mfma_f32_16x16x32_bf16 v[12:15], v[164:167], v[196:199], v[12:15]
	v_mfma_f32_16x16x32_bf16 v[12:15], v[168:171], v[200:203], v[12:15]
	v_mfma_f32_16x16x32_bf16 v[8:11], v[176:179], v[200:203], v[8:11]
	v_mfma_f32_16x16x32_bf16 v[8:11], v[172:175], v[196:199], v[8:11]
	v_mfma_f32_16x16x32_bf16 v[0:3], v[172:175], v[204:207], v[0:3]
	v_mfma_f32_16x16x32_bf16 v[0:3], v[176:179], v[208:211], v[0:3]
	v_mfma_f32_16x16x32_bf16 v[4:7], v[168:171], v[208:211], v[4:7]
	v_mfma_f32_16x16x32_bf16 v[4:7], v[164:167], v[204:207], v[4:7]
	s_setprio 0
	s_barrier
	s_add_i32 s50, 0, 0x18000
	s_add_i32 s51, 0, 0x1c000
	v_add_u32_e32 v160, s50, v147
	v_add_u32_e32 v176, s51, v147
	ds_read_b128 v[140:143], v160
	ds_read_b128 v[152:155], v160 offset:1024
	ds_read_b128 v[156:159], v160 offset:2048
	ds_read_b128 v[160:163], v160 offset:3072
	ds_read_b128 v[164:167], v176
	ds_read_b128 v[168:171], v176 offset:1024
	ds_read_b128 v[172:175], v176 offset:2048
	ds_read_b128 v[176:179], v176 offset:3072
	s_add_u32 s34, s34, 0x80000
	s_addc_u32 s35, s35, 0
	s_mov_b32 m0, s37
	v_lshl_add_u64 v[218:219], s[34:35], 0, v[128:129]
	ds_read_b128 v[180:183], v151 offset:32768
	ds_read_b128 v[184:187], v151 offset:33792
	ds_read_b128 v[188:191], v151 offset:34816
	ds_read_b128 v[192:195], v151 offset:35840
	ds_read_b128 v[196:199], v151 offset:36864
	ds_read_b128 v[200:203], v151 offset:37888
	ds_read_b128 v[204:207], v151 offset:38912
	ds_read_b128 v[208:211], v151 offset:39936
	global_load_lds_dwordx4 v[218:219], off
	v_lshl_add_u64 v[218:219], s[34:35], 0, v[130:131]
	s_mov_b32 m0, s38
	s_nop 0
	global_load_lds_dwordx4 v[218:219], off
	s_waitcnt vmcnt(8)
	s_waitcnt lgkmcnt(0)
	s_barrier
	s_setprio 1
	s_waitcnt lgkmcnt(0)
	v_mfma_f32_16x16x32_bf16 v[124:127], v[140:143], v[180:183], v[124:127]
	v_mfma_f32_16x16x32_bf16 v[124:127], v[152:155], v[184:187], v[124:127]
	v_mfma_f32_16x16x32_bf16 v[120:123], v[160:163], v[184:187], v[120:123]
	v_mfma_f32_16x16x32_bf16 v[120:123], v[156:159], v[180:183], v[120:123]
	v_mfma_f32_16x16x32_bf16 v[112:115], v[156:159], v[188:191], v[112:115]
	v_mfma_f32_16x16x32_bf16 v[112:115], v[160:163], v[192:195], v[112:115]
	v_mfma_f32_16x16x32_bf16 v[116:119], v[152:155], v[192:195], v[116:119]
	v_mfma_f32_16x16x32_bf16 v[116:119], v[140:143], v[188:191], v[116:119]
	v_mfma_f32_16x16x32_bf16 v[108:111], v[140:143], v[196:199], v[108:111]
	v_mfma_f32_16x16x32_bf16 v[108:111], v[152:155], v[200:203], v[108:111]
	v_mfma_f32_16x16x32_bf16 v[100:103], v[160:163], v[200:203], v[100:103]
	v_mfma_f32_16x16x32_bf16 v[100:103], v[156:159], v[196:199], v[100:103]
	v_mfma_f32_16x16x32_bf16 v[80:83], v[156:159], v[204:207], v[80:83]
	v_mfma_f32_16x16x32_bf16 v[80:83], v[160:163], v[208:211], v[80:83]
	v_mfma_f32_16x16x32_bf16 v[92:95], v[152:155], v[208:211], v[92:95]
	v_mfma_f32_16x16x32_bf16 v[92:95], v[140:143], v[204:207], v[92:95]
	s_setprio 0
	s_setprio 1
	v_mfma_f32_16x16x32_bf16 v[104:107], v[164:167], v[180:183], v[104:107]
	v_mfma_f32_16x16x32_bf16 v[104:107], v[168:171], v[184:187], v[104:107]
	v_mfma_f32_16x16x32_bf16 v[96:99], v[176:179], v[184:187], v[96:99]
	v_mfma_f32_16x16x32_bf16 v[96:99], v[172:175], v[180:183], v[96:99]
	v_mfma_f32_16x16x32_bf16 v[84:87], v[172:175], v[188:191], v[84:87]
	v_mfma_f32_16x16x32_bf16 v[84:87], v[176:179], v[192:195], v[84:87]
	v_mfma_f32_16x16x32_bf16 v[88:91], v[168:171], v[192:195], v[88:91]
	v_mfma_f32_16x16x32_bf16 v[88:91], v[164:167], v[188:191], v[88:91]
	v_mfma_f32_16x16x32_bf16 v[76:79], v[164:167], v[196:199], v[76:79]
	v_mfma_f32_16x16x32_bf16 v[76:79], v[168:171], v[200:203], v[76:79]
	v_mfma_f32_16x16x32_bf16 v[72:75], v[176:179], v[200:203], v[72:75]
	v_mfma_f32_16x16x32_bf16 v[72:75], v[172:175], v[196:199], v[72:75]
	v_mfma_f32_16x16x32_bf16 v[64:67], v[172:175], v[204:207], v[64:67]
	v_mfma_f32_16x16x32_bf16 v[64:67], v[176:179], v[208:211], v[64:67]
	v_mfma_f32_16x16x32_bf16 v[68:71], v[168:171], v[208:211], v[68:71]
	v_mfma_f32_16x16x32_bf16 v[68:71], v[164:167], v[204:207], v[68:71]
	s_setprio 0
	s_barrier
; #define PG8_STAGE(bufoff, gbase, voff) do { _Pragma("unroll") for (int _i = 0; _i < 2; ++_i) \
;         __builtin_amdgcn_global_load_lds((const unsigned*)((const char*)(gbase) + (voff)[_i]), (PG8_LAS unsigned*)(lds + (bufoff) + ldsw + _i * 8192), 16, 0, 0); } while (0)
; #define PG8_LDA(dst, b, h) do { _Pragma("unroll") for (int m = 0; m < 4; ++m) _Pragma("unroll") for (int k = 0; k < 2; ++k) dst[m][k] = *(const PG8_LAS bf16x8*)(lds + PG8_SA(b, h) + aoff + m * 2048 + k * 1024); } while (0)
; #define PG8_MMA(ai, bj, At, Bt) do { __builtin_amdgcn_s_setprio(1); _Pragma("unroll") for (int m = 0; m < 4; ++m) _Pragma("unroll") for (int n = 0; n < 2; ++n) _Pragma("unroll") for (int k = 0; k < 2; ++k) \
;         acc[ai][bj][m][n] = __builtin_amdgcn_mfma_f32_16x16x32_bf16(Bt[n][k], At[m][k], acc[ai][bj][m][n], 0, 0, 0); __builtin_amdgcn_s_setprio(0); } while (0)
; #define PG8_WAIT_V(n) asm volatile("s_waitcnt vmcnt(" #n ")" ::: "memory")
; #define PG8_WAIT_L(n) asm volatile("s_waitcnt lgkmcnt(" #n ")" ::: "memory")
; #define PG8_BAR __builtin_amdgcn_s_barrier()
; #define PG8_SCHED __builtin_amdgcn_sched_barrier(0)
; template <class Epi, class Sched, bool ALIGN_EPI = false, bool SP2 = false>
; __device__ __forceinline__ void gemm_phase(PG8_LAS unsigned char* lds, const Gemm g, const Sched& S, const Epi& E) {
;     ...
;         for (int t = 0; t < nt; t += 2) {
;     ...
;             PG8_LDA(At, 1, 1); PG8_STAGE(PG8_SB(1, 0), b3, voffB); PG8_STAGE(PG8_SB(1, 1), b3 + hstep, voffB); PG8_STAGE(PG8_SA(1, 0), a3, voffA);
;             PG8_WAIT_V(8); PG8_WAIT_L(0); PG8_BAR; PG8_MMA(1, 0, At, B0); PG8_MMA(1, 1, At, B1); PG8_BAR; PG8_SCHED;
	s_add_i32 s34, s50, s30
	v_lshl_add_u64 v[144:145], v[144:145], 0, s[4:5]
	s_mov_b32 m0, s34
	ds_read_b128 v[180:183], v151 offset:49152
	ds_read_b128 v[184:187], v151 offset:50176
	ds_read_b128 v[188:191], v151 offset:51200
	ds_read_b128 v[192:195], v151 offset:52224
	ds_read_b128 v[196:199], v151 offset:53248
	ds_read_b128 v[200:203], v151 offset:54272
	ds_read_b128 v[204:207], v151 offset:55296
	ds_read_b128 v[208:211], v151 offset:56320
	global_load_lds_dwordx4 v[144:145], off
	s_add_i32 m0, s34, 0x2000
	s_add_u32 s28, s28, 0x80080
	v_lshl_add_u64 v[144:145], v[212:213], 0, s[4:5]
	s_addc_u32 s29, s29, 0
	s_add_i32 s34, s51, s30
	global_load_lds_dwordx4 v[144:145], off
	v_lshl_add_u64 v[144:145], s[28:29], 0, v[128:129]
	s_mov_b32 m0, s34
	s_nop 0
	global_load_lds_dwordx4 v[144:145], off
	v_lshl_add_u64 v[144:145], s[28:29], 0, v[130:131]
	s_add_i32 m0, s34, 0x2000
	s_nop 0
	global_load_lds_dwordx4 v[144:145], off
	v_lshl_add_u64 v[144:145], v[214:215], 0, s[4:5]
	s_mov_b32 m0, s41
	s_nop 0
	global_load_lds_dwordx4 v[144:145], off
	v_lshl_add_u64 v[144:145], v[216:217], 0, s[4:5]
	s_mov_b32 m0, s42
	s_nop 0
	global_load_lds_dwordx4 v[144:145], off
	s_waitcnt vmcnt(8)
	s_waitcnt lgkmcnt(0)
	s_barrier
	s_setprio 1
	s_waitcnt lgkmcnt(0)
	v_mfma_f32_16x16x32_bf16 v[60:63], v[140:143], v[180:183], v[60:63]
	v_mfma_f32_16x16x32_bf16 v[60:63], v[152:155], v[184:187], v[60:63]
	v_mfma_f32_16x16x32_bf16 v[56:59], v[160:163], v[184:187], v[56:59]
	v_mfma_f32_16x16x32_bf16 v[56:59], v[156:159], v[180:183], v[56:59]
	v_mfma_f32_16x16x32_bf16 v[48:51], v[156:159], v[188:191], v[48:51]
	v_mfma_f32_16x16x32_bf16 v[48:51], v[160:163], v[192:195], v[48:51]
	v_mfma_f32_16x16x32_bf16 v[52:55], v[152:155], v[192:195], v[52:55]
	v_mfma_f32_16x16x32_bf16 v[52:55], v[140:143], v[188:191], v[52:55]
	v_mfma_f32_16x16x32_bf16 v[44:47], v[140:143], v[196:199], v[44:47]
	v_mfma_f32_16x16x32_bf16 v[44:47], v[152:155], v[200:203], v[44:47]
	v_mfma_f32_16x16x32_bf16 v[36:39], v[160:163], v[200:203], v[36:39]
	v_mfma_f32_16x16x32_bf16 v[36:39], v[156:159], v[196:199], v[36:39]
	v_mfma_f32_16x16x32_bf16 v[16:19], v[156:159], v[204:207], v[16:19]
	v_mfma_f32_16x16x32_bf16 v[16:19], v[160:163], v[208:211], v[16:19]
	v_mfma_f32_16x16x32_bf16 v[28:31], v[152:155], v[208:211], v[28:31]
	v_mfma_f32_16x16x32_bf16 v[28:31], v[140:143], v[204:207], v[28:31]
	s_setprio 0
	s_setprio 1
	v_mfma_f32_16x16x32_bf16 v[40:43], v[164:167], v[180:183], v[40:43]
	v_mfma_f32_16x16x32_bf16 v[40:43], v[168:171], v[184:187], v[40:43]
	v_mfma_f32_16x16x32_bf16 v[32:35], v[176:179], v[184:187], v[32:35]
	v_mfma_f32_16x16x32_bf16 v[32:35], v[172:175], v[180:183], v[32:35]
	v_mfma_f32_16x16x32_bf16 v[20:23], v[172:175], v[188:191], v[20:23]
	v_mfma_f32_16x16x32_bf16 v[20:23], v[176:179], v[192:195], v[20:23]
	v_mfma_f32_16x16x32_bf16 v[24:27], v[168:171], v[192:195], v[24:27]
	v_mfma_f32_16x16x32_bf16 v[24:27], v[164:167], v[188:191], v[24:27]
	v_mfma_f32_16x16x32_bf16 v[12:15], v[164:167], v[196:199], v[12:15]
	v_mfma_f32_16x16x32_bf16 v[12:15], v[168:171], v[200:203], v[12:15]
	v_mfma_f32_16x16x32_bf16 v[8:11], v[176:179], v[200:203], v[8:11]
	v_mfma_f32_16x16x32_bf16 v[8:11], v[172:175], v[196:199], v[8:11]
	v_mfma_f32_16x16x32_bf16 v[0:3], v[172:175], v[204:207], v[0:3]
	v_mfma_f32_16x16x32_bf16 v[0:3], v[176:179], v[208:211], v[0:3]
	v_mfma_f32_16x16x32_bf16 v[4:7], v[168:171], v[208:211], v[4:7]
	v_mfma_f32_16x16x32_bf16 v[4:7], v[164:167], v[204:207], v[4:7]
	s_setprio 0
	s_barrier
	s_add_i32 s49, s49, 2
	s_add_u32 s26, s26, 0x100
	s_addc_u32 s27, s27, 0
	s_add_u32 s47, s47, 0x100
	s_addc_u32 s48, s48, 0
	s_cmp_gt_u32 s49, 29
	s_cbranch_scc0 .LBB0_458
	s_and_b64 vcc, exec, s[6:7]
	s_cbranch_vccz .LBB0_461
	s_barrier
